# grid barrier: last XCD leader bumps all per-XCD generation words directly (one polling hop fewer on release)
# speedup vs baseline: 1.0140x; 1.0035x over previous
.LBB0_117:
	s_or_b64 exec, exec, s[12:13]
	s_and_saveexec_b64 s[12:13], s[16:17]
	s_cbranch_execz .LBB0_119
	v_mov_b32_e32 v2, 1
	global_atomic_add v[0:1], v2, off
	v_readlane_b32 s98, v246, 3
	v_readlane_b32 s99, v246, 4
	v_mov_b32_e32 v3, 0x2400
	v_mov_b32_e32 v4, 0x2500
	v_mov_b32_e32 v5, 0x2600
	v_mov_b32_e32 v6, 0x2700
	v_mov_b32_e32 v7, 0x2800
	v_mov_b32_e32 v8, 0x2900
	v_mov_b32_e32 v9, 0x2a00
	v_mov_b32_e32 v10, 0x2b00
	global_atomic_add v3, v2, s[98:99]
	global_atomic_add v4, v2, s[98:99]
	global_atomic_add v5, v2, s[98:99]
	global_atomic_add v6, v2, s[98:99]
	global_atomic_add v7, v2, s[98:99]
	global_atomic_add v8, v2, s[98:99]
	global_atomic_add v9, v2, s[98:99]
	global_atomic_add v10, v2, s[98:99]
.LBB0_119:
	s_or_b64 exec, exec, s[12:13]
	v_mov_b32_e32 v0, 0x2000
	v_mov_b32_e32 v1, 1
	s_waitcnt vmcnt(0)
	buffer_inv sc1
	s_waitcnt vmcnt(0)

.LBB0_179:
	s_or_b64 exec, exec, s[10:11]
	s_and_saveexec_b64 s[10:11], s[14:15]
	s_cbranch_execz .LBB0_181
	v_mov_b32_e32 v2, 1
	global_atomic_add v[0:1], v2, off
	v_readlane_b32 s98, v246, 3
	v_readlane_b32 s99, v246, 4
	v_mov_b32_e32 v3, 0x2400
	v_mov_b32_e32 v4, 0x2500
	v_mov_b32_e32 v5, 0x2600
	v_mov_b32_e32 v6, 0x2700
	v_mov_b32_e32 v7, 0x2800
	v_mov_b32_e32 v8, 0x2900
	v_mov_b32_e32 v9, 0x2a00
	v_mov_b32_e32 v10, 0x2b00
	global_atomic_add v3, v2, s[98:99]
	global_atomic_add v4, v2, s[98:99]
	global_atomic_add v5, v2, s[98:99]
	global_atomic_add v6, v2, s[98:99]
	global_atomic_add v7, v2, s[98:99]
	global_atomic_add v8, v2, s[98:99]
	global_atomic_add v9, v2, s[98:99]
	global_atomic_add v10, v2, s[98:99]
.LBB0_181:
	s_or_b64 exec, exec, s[10:11]
	v_mov_b32_e32 v0, 0x2000
	v_mov_b32_e32 v1, 1
	s_waitcnt vmcnt(0)
	buffer_inv sc1
	s_waitcnt vmcnt(0)

.LBB0_252:
	s_or_b64 exec, exec, s[8:9]
	s_and_saveexec_b64 s[8:9], s[12:13]
	s_cbranch_execz .LBB0_254
	v_mov_b32_e32 v2, 1
	global_atomic_add v[0:1], v2, off
	v_readlane_b32 s98, v246, 3
	v_readlane_b32 s99, v246, 4
	v_mov_b32_e32 v3, 0x2400
	v_mov_b32_e32 v4, 0x2500
	v_mov_b32_e32 v5, 0x2600
	v_mov_b32_e32 v6, 0x2700
	v_mov_b32_e32 v7, 0x2800
	v_mov_b32_e32 v8, 0x2900
	v_mov_b32_e32 v9, 0x2a00
	v_mov_b32_e32 v10, 0x2b00
	global_atomic_add v3, v2, s[98:99]
	global_atomic_add v4, v2, s[98:99]
	global_atomic_add v5, v2, s[98:99]
	global_atomic_add v6, v2, s[98:99]
	global_atomic_add v7, v2, s[98:99]
	global_atomic_add v8, v2, s[98:99]
	global_atomic_add v9, v2, s[98:99]
	global_atomic_add v10, v2, s[98:99]
.LBB0_254:
	s_or_b64 exec, exec, s[8:9]
	v_mov_b32_e32 v0, 0x2000
	v_mov_b32_e32 v1, 1
	s_waitcnt vmcnt(0)
	buffer_inv sc1
	s_waitcnt vmcnt(0)

.LBB0_618:
	s_or_b64 exec, exec, s[8:9]
	s_and_saveexec_b64 s[8:9], s[14:15]
	s_cbranch_execz .LBB0_620
	v_mov_b32_e32 v2, 1
	global_atomic_add v[0:1], v2, off
	v_readlane_b32 s98, v246, 3
	v_readlane_b32 s99, v246, 4
	v_mov_b32_e32 v3, 0x2400
	v_mov_b32_e32 v4, 0x2500
	v_mov_b32_e32 v5, 0x2600
	v_mov_b32_e32 v6, 0x2700
	v_mov_b32_e32 v7, 0x2800
	v_mov_b32_e32 v8, 0x2900
	v_mov_b32_e32 v9, 0x2a00
	v_mov_b32_e32 v10, 0x2b00
	global_atomic_add v3, v2, s[98:99]
	global_atomic_add v4, v2, s[98:99]
	global_atomic_add v5, v2, s[98:99]
	global_atomic_add v6, v2, s[98:99]
	global_atomic_add v7, v2, s[98:99]
	global_atomic_add v8, v2, s[98:99]
	global_atomic_add v9, v2, s[98:99]
	global_atomic_add v10, v2, s[98:99]

.LBB0_873:
	s_or_b64 exec, exec, s[8:9]
	s_and_saveexec_b64 s[8:9], s[20:21]
	s_cbranch_execz .LBB0_875
	v_mov_b32_e32 v2, 1
	global_atomic_add v[0:1], v2, off
	v_readlane_b32 s98, v246, 3
	v_readlane_b32 s99, v246, 4
	v_mov_b32_e32 v3, 0x2400
	v_mov_b32_e32 v4, 0x2500
	v_mov_b32_e32 v5, 0x2600
	v_mov_b32_e32 v6, 0x2700
	v_mov_b32_e32 v7, 0x2800
	v_mov_b32_e32 v8, 0x2900
	v_mov_b32_e32 v9, 0x2a00
	v_mov_b32_e32 v10, 0x2b00
	global_atomic_add v3, v2, s[98:99]
	global_atomic_add v4, v2, s[98:99]
	global_atomic_add v5, v2, s[98:99]
	global_atomic_add v6, v2, s[98:99]
	global_atomic_add v7, v2, s[98:99]
	global_atomic_add v8, v2, s[98:99]
	global_atomic_add v9, v2, s[98:99]
	global_atomic_add v10, v2, s[98:99]

	.amdhsa_kernel _Z14fwd_megakernel4Args
		.amdhsa_group_segment_fixed_size 0
		.amdhsa_private_segment_fixed_size 0
		.amdhsa_kernarg_size 544
		.amdhsa_user_sgpr_count 2
		.amdhsa_user_sgpr_dispatch_ptr 0
		.amdhsa_user_sgpr_queue_ptr 0
		.amdhsa_user_sgpr_kernarg_segment_ptr 1
		.amdhsa_user_sgpr_dispatch_id 0
		.amdhsa_user_sgpr_kernarg_preload_length 0
		.amdhsa_user_sgpr_kernarg_preload_offset 0
		.amdhsa_user_sgpr_private_segment_size 0
		.amdhsa_uses_dynamic_stack 0
		.amdhsa_enable_private_segment 0
		.amdhsa_system_sgpr_workgroup_id_x 1
		.amdhsa_system_sgpr_workgroup_id_y 0
		.amdhsa_system_sgpr_workgroup_id_z 0
		.amdhsa_system_sgpr_workgroup_info 0
		.amdhsa_system_vgpr_workitem_id 2
		.amdhsa_next_free_vgpr 247
		.amdhsa_next_free_sgpr 100
		.amdhsa_accum_offset 248
		.amdhsa_reserve_vcc 1
		.amdhsa_float_round_mode_32 0
		.amdhsa_float_round_mode_16_64 0
		.amdhsa_float_denorm_mode_32 3
		.amdhsa_float_denorm_mode_16_64 3
		.amdhsa_dx10_clamp 1
		.amdhsa_ieee_mode 1
		.amdhsa_fp16_overflow 0
		.amdhsa_tg_split 0
		.amdhsa_exception_fp_ieee_invalid_op 0
		.amdhsa_exception_fp_denorm_src 0
		.amdhsa_exception_fp_ieee_div_zero 0
		.amdhsa_exception_fp_ieee_overflow 0
		.amdhsa_exception_fp_ieee_underflow 0
		.amdhsa_exception_fp_ieee_inexact 0
		.amdhsa_exception_int_div_zero 0
	.end_amdhsa_kernel

amdhsa.kernels:
  - .agpr_count:     0
    .args:
      - .offset:         0
        .size:           288
        .value_kind:     by_value
      - .offset:         288
        .size:           4
        .value_kind:     hidden_block_count_x
      - .offset:         292
        .size:           4
        .value_kind:     hidden_block_count_y
      - .offset:         296
        .size:           4
        .value_kind:     hidden_block_count_z
      - .offset:         300
        .size:           2
        .value_kind:     hidden_group_size_x
      - .offset:         302
        .size:           2
        .value_kind:     hidden_group_size_y
      - .offset:         304
        .size:           2
        .value_kind:     hidden_group_size_z
      - .offset:         306
        .size:           2
        .value_kind:     hidden_remainder_x
      - .offset:         308
        .size:           2
        .value_kind:     hidden_remainder_y
      - .offset:         310
        .size:           2
        .value_kind:     hidden_remainder_z
      - .offset:         328
        .size:           8
        .value_kind:     hidden_global_offset_x
      - .offset:         336
        .size:           8
        .value_kind:     hidden_global_offset_y
      - .offset:         344
        .size:           8
        .value_kind:     hidden_global_offset_z
      - .offset:         352
        .size:           2
        .value_kind:     hidden_grid_dims
      - .offset:         376
        .size:           8
        .value_kind:     hidden_multigrid_sync_arg
      - .offset:         408
        .size:           4
        .value_kind:     hidden_dynamic_lds_size
    .group_segment_fixed_size: 0
    .kernarg_segment_align: 8
    .kernarg_segment_size: 544
    .language:       OpenCL C
    .language_version:
      - 2
      - 0
    .max_flat_workgroup_size: 512
    .name:           _Z14fwd_megakernel4Args
    .private_segment_fixed_size: 0
    .sgpr_count:     106
    .sgpr_spill_count: 27
    .symbol:         _Z14fwd_megakernel4Args.kd
    .uniform_work_group_size: 1
    .uses_dynamic_stack: false
    .vgpr_count:     247
    .vgpr_spill_count: 0
    .wavefront_size: 64
